# plus: input-projection column tiles interleaved across the two XCD halves (balances the q/k/v epilogues)
# baseline (speedup 1.0000x reference)
;     __device__ __forceinline__ bool next(int i, Unit& u) const {
;         const long L = (long)i * G + c; if (L >= nwg + extra) return false;
;         u.ks = 0; u.kt0 = 0; u.nt = ntfull;
;         if (L >= nwg) { const int e = (int)L - nwg;
;             if (extra == 32) { u.pm = 32 + (e & 3); u.pn = 4 + (e >> 2); }
;             else { u.ks = e & 3; u.pm = 32 + ((e >> 2) & 3); u.pn = e >> 4; u.nt = ntfull >> 2; u.kt0 = u.ks * u.nt; }
;             return true; }
;         int wgid = (int)L; { const int q = nwg / NXCD, r = nwg % NXCD, xcd = wgid % NXCD, off = wgid / NXCD; wgid = (xcd < r ? xcd * (q + 1) : r * (q + 1) + (xcd - r) * q) + off; }
;         const int nig = wgm * nN, gid = wgid / nig, fm = gid * wgm, gsz = (nM - fm) < wgm ? (nM - fm) : wgm;
;         u.pm = fm + ((wgid % nig) % gsz); u.pn = (wgid % nig) / gsz; return true;
;     }
.LBB0_11:
	s_and_b32 s2, s8, 0xffffffc0
	s_waitcnt lgkmcnt(0)
	s_add_u32 s48, s0, 0x30abc000
	s_addc_u32 s49, s1, 0
	s_cmpk_lt_i32 s33, 0x400
	s_cselect_b64 s[4:5], -1, 0
	v_writelane_b32 v253, s4, 2
	s_cmpk_lt_i32 s33, 0x200
	s_movk_i32 s77, 0x71
	v_writelane_b32 v253, s5, 3
	s_cselect_b64 s[4:5], -1, 0
	s_cmpk_lt_i32 s33, 0x100
	v_writelane_b32 v253, s4, 4
	s_cselect_b64 s[58:59], -1, 0
	s_cmpk_gt_i32 s33, 0xff
	v_writelane_b32 v253, s5, 5
	s_cselect_b64 s[4:5], -1, 0
	s_lshl_b32 s60, s33, 9
	s_lshl_b32 s50, s42, 9
	v_writelane_b32 v253, s4, 6
	s_cmpk_lt_i32 s33, 0x3a0
	v_lshrrev_b32_e32 v1, 20, v0
	v_writelane_b32 v253, s5, 7
	s_cselect_b64 s[4:5], -1, 0
	v_writelane_b32 v253, s4, 8
	s_ashr_i32 s96, s33, 31
	s_add_i32 s1, s33, 0xfffffc80
	v_writelane_b32 v253, s5, 9
	s_lshr_b32 s4, s96, 29
	s_add_i32 s4, s33, s4
	s_ashr_i32 s61, s4, 3
	s_and_b32 s4, s4, -8
	s_bfe_u32 s5, s33, 0x20002
	s_sub_i32 s62, s33, s4
	s_add_i32 s4, s33, 0xffffff00
	s_or_b32 s5, s5, 32
	v_writelane_b32 v253, s5, 10
	s_lshr_b32 s4, s4, 4
	s_and_b32 s6, s33, 3
	v_writelane_b32 v253, s4, 11
	s_lshr_b32 s1, s1, 2
	v_writelane_b32 v253, s6, 12
	s_lshl_b32 s4, s6, 6
	s_or_b32 s3, s6, 32
	s_add_i32 s1, s1, 4
	s_ashr_i32 s63, s42, 31
	v_writelane_b32 v253, s4, 13
	s_lshl_b32 s4, s62, 5
	s_lshl_b32 s10, s33, 3
	s_cmp_lt_i32 s62, 0
	s_cselect_b32 s6, s77, 0x70
	s_mul_i32 s5, s62, 33
	s_mul_i32 s6, s62, s6
	s_cselect_b32 s4, s5, s4
	s_add_i32 s6, s6, s61
	s_mul_hi_i32 s5, s6, 0x92492493
	s_add_i32 s5, s5, s6
	s_lshr_b32 s7, s5, 31
	s_ashr_i32 s5, s5, 7
	s_add_i32 s5, s5, s7
	s_mul_i32 s7, s5, 0xe0
	s_sub_i32 s6, s6, s7
	s_bfe_u32 s7, s6, 0x3001c
	s_add_i32 s7, s6, s7
	s_sext_i32_i16 s8, s7
	s_and_b32 s7, s7, 0xfff8
	s_add_i32 s4, s4, s61
	s_sub_i32 s6, s6, s7
	s_ashr_i32 s7, s4, 31
	s_lshr_b32 s7, s7, 27
	s_lshl_b32 s5, s5, 3
	s_sext_i32_i16 s6, s6
	s_add_i32 s7, s4, s7
	s_add_i32 s5, s5, s6
	s_ashr_i32 s6, s8, 3
	s_ashr_i32 s8, s7, 5
	s_and_b32 s7, s7, 0xffe0
	s_sub_i32 s4, s4, s7
	s_bfe_i32 s7, s4, 0x80000
	s_bfe_u32 s7, s7, 0x2000d
	s_add_i32 s7, s4, s7
	s_bfe_i32 s9, s7, 0x80000
	s_and_b32 s7, s7, 0xfc
	s_sub_i32 s4, s4, s7
	s_lshl_b32 s8, s8, 2
	s_sext_i32_i8 s4, s4
	s_sext_i32_i16 s9, s9
	s_add_i32 s4, s8, s4
	v_writelane_b32 v253, s4, 14
	s_ashr_i32 s4, s9, 2
	s_lshr_b32 s86, s62, 31
	s_cmpk_gt_i32 s33, 0x37f
	v_lshrrev_b32_e32 v0, 10, v0
	v_writelane_b32 v253, s4, 15
	s_cselect_b32 s4, s3, s5
	s_cselect_b32 s6, s1, s6
	s_cmpk_gt_i32 s33, 0x37f
	s_cbranch_scc1 .Lin_pn0_done
	s_sub_i32 s98, s6, 14
	s_cmp_lt_i32 s6, 14
	s_cselect_b32 s98, s6, s98
	s_cselect_b32 s99, 0, 1
	s_lshl_b32 s98, s98, 1
	s_or_b32 s6, s98, s99
.Lin_pn0_done:
	s_abs_i32 s87, s42
	v_or_b32_e32 v0, v0, v1
	s_movk_i32 s1, 0x3ff
	s_barrier
	v_cvt_f32_u32_e32 v3, s87
	v_and_or_b32 v0, v0, s1, v2
	s_load_dword s1, s[44:45], 0xd8
	s_mul_i32 s0, s43, s42
	v_rcp_iflag_f32_e32 v1, v3
	s_ashr_i32 s5, s4, 31
	s_ashr_i32 s7, s6, 31
	s_waitcnt lgkmcnt(0)
	s_mul_i32 s89, s0, s1
	s_mov_b32 s0, s4
	v_writelane_b32 v253, s0, 16
	v_mul_f32_e32 v1, 0x4f7ffffe, v1
	v_cvt_u32_f32_e32 v1, v1
	v_writelane_b32 v253, s1, 17
	s_lshl_b64 s[0:1], s[4:5], 20
	v_writelane_b32 v253, s0, 18
	s_mov_b32 s38, 0x6dc9c883
	s_mov_b32 s84, 0x54442d18
	v_writelane_b32 v253, s1, 19
	s_mov_b32 s0, s6
	v_writelane_b32 v253, s0, 20
	v_mbcnt_hi_u32_b32 v220, -1, v8
	s_movk_i32 s68, 0x800
	v_writelane_b32 v253, s1, 21
	s_lshl_b64 s[0:1], s[6:7], 20
	v_writelane_b32 v253, s0, 22
	s_mov_b32 s69, 0x10000
	s_mov_b32 s92, 0x12000
	v_writelane_b32 v253, s1, 23
	s_sub_i32 s0, 0, s87
	v_readfirstlane_b32 s1, v1
	s_mul_i32 s0, s0, s1
	s_mul_hi_u32 s0, s1, s0
	s_add_i32 s91, s1, s0
	s_mul_hi_u32 s0, s91, 0x3a0
	s_mul_i32 s0, s0, s87
	s_sub_i32 s0, 0x3a0, s0
	s_sub_i32 s1, s0, s87
	s_cmp_ge_u32 s0, s87
	s_cselect_b32 s0, s1, s0
	s_sub_i32 s1, s0, s87
	s_cmp_ge_u32 s0, s87
	s_cselect_b32 s0, s1, s0
	v_writelane_b32 v253, s0, 24
	s_lshl_b32 s0, s33, 8
	v_writelane_b32 v253, s0, 25
	s_lshl_b32 s0, s42, 8
	v_writelane_b32 v253, s0, 26
	s_lshl_b32 s0, s33, 4
	v_writelane_b32 v253, s0, 27
	s_lshl_b32 s0, s33, 12
	v_writelane_b32 v253, s0, 28
	s_lshl_b32 s0, s42, 12
	v_writelane_b32 v253, s0, 29
	s_ashr_i32 s11, s10, 31
	v_writelane_b32 v253, s10, 30
	s_lshl_b32 s0, s42, 1
	s_lshl_b32 s52, s42, 3
	v_writelane_b32 v253, s11, 31
	v_writelane_b32 v253, s0, 32
	s_add_i32 s0, 0, 0x2000
	v_writelane_b32 v253, s0, 33
	s_add_i32 s0, 0, 0x11000
	v_writelane_b32 v253, s0, 34
	s_add_i32 s0, 0, 0x20004
	v_writelane_b32 v253, s0, 35
	s_mov_b32 s0, 0
	v_writelane_b32 v253, s0, 36
	v_cmp_eq_u32_e64 s[0:1], 0, v0
	s_ashr_i32 s53, s52, 31
	s_ashr_i32 s51, s50, 31
	v_writelane_b32 v253, s0, 37
	s_lshl_b32 s97, s42, 4
	v_mov_b32_e32 v1, 0
	v_writelane_b32 v253, s1, 38
	s_lshl_b64 s[0:1], s[52:53], 12
	v_writelane_b32 v253, s0, 39
	s_movk_i32 s41, 0x2000
	s_mov_b32 s36, 0xbfb8aa3b
	v_writelane_b32 v253, s1, 40
	s_mov_b32 s93, 0x42ce8ed0
	s_mov_b32 s37, 0xc2b17218
	v_mov_b32_e32 v246, 0x3ecc95a3
	v_mov_b32_e32 v247, 0x3727c5ac
	v_mov_b32_e32 v216, 0x260
	v_mov_b32_e32 v217, 0x358637bd
	s_mov_b32 s39, 0x3fe45f30
	s_mov_b32 s85, 0xbff921fb
	v_add_u32_e32 v221, s2, v220
	v_mov_b32_e32 v222, 0x7f800000
	v_mov_b32_e32 v162, 0x3f317218
	v_mov_b32_e32 v164, 0x67f544e4
	v_mov_b32_e32 v166, 0xa556c734
	v_mov_b32_e32 v168, 0x1a01a01a
	v_mov_b32_e32 v170, 0x11111111
	v_mov_b32_e32 v172, 0x55555555
	v_mov_b32_e32 v174, 0xeff8d898
	v_mov_b32_e32 v176, 0xb7789f5c
	v_mov_b32_e32 v179, 0x3efa01a0
	v_mov_b32_e32 v180, 0x16c16c17
	v_mov_b32_e32 v183, 0x3fa55555
	v_mov_b32_e32 v223, 0xb00
	v_mov_b32_e32 v165, 0xbe5ae645
	v_mov_b32_e32 v167, 0x3ec71de3
	v_mov_b32_e32 v169, 0xbf2a01a0
	v_mov_b32_e32 v171, 0x3f811111
	v_mov_b32_e32 v173, 0xbfc55555
	v_mov_b32_e32 v175, 0x3e21eed8
	v_mov_b32_e32 v177, 0xbe927e4f
	v_mov_b32_e32 v181, 0xbf56c16c
	s_mov_b32 s35, 0x3f2aaaab
	s_mov_b32 s40, 0xf800000
	s_mov_b32 s28, 0x20000
	s_movk_i32 s95, 0x2c00
	s_movk_i32 s94, 0x1fff
	s_mov_b32 s88, 0
	s_lshl_b64 s[66:67], s[50:51], 2
	s_mov_b64 s[70:71], 0x80
	s_mov_b64 s[72:73], 0x100
	s_mov_b64 s[74:75], 0x120000
	s_mov_b32 s76, 0x3db504f3
	v_writelane_b32 v253, s86, 41
	s_branch .LBB0_14

;     __device__ __forceinline__ bool next(int i, Unit& u) const {
;     ...
;         int wgid = (int)L; { const int q = nwg / NXCD, r = nwg % NXCD, xcd = wgid % NXCD, off = wgid / NXCD; wgid = (xcd < r ? xcd * (q + 1) : r * (q + 1) + (xcd - r) * q) + off; }
;         const int nig = wgm * nN, gid = wgid / nig, fm = gid * wgm, gsz = (nM - fm) < wgm ? (nM - fm) : wgm;
;         u.pm = fm + ((wgid % nig) % gsz); u.pn = (wgid % nig) / gsz; return true;
.LBB0_133:
	s_andn2_b64 vcc, exec, s[0:1]
	s_cbranch_vccnz .LBB0_135
	s_ashr_i32 s0, s8, 31
	s_lshr_b32 s0, s0, 29
	s_add_i32 s0, s8, s0
	s_ashr_i32 s1, s0, 3
	s_and_b32 s0, s0, -8
	s_sub_i32 s0, s8, s0
	s_cmp_lt_i32 s0, 0
	s_cselect_b32 s12, s77, 0x70
	s_mul_i32 s0, s0, s12
	s_add_i32 s0, s0, s1
	s_mul_hi_i32 s1, s0, 0x92492493
	s_add_i32 s1, s1, s0
	s_lshr_b32 s12, s1, 31
	s_ashr_i32 s1, s1, 7
	s_add_i32 s1, s1, s12
	s_lshl_b32 s12, s1, 3
	s_sub_i32 s13, 32, s12
	s_min_i32 s13, s13, 8
	s_abs_i32 s14, s13
	v_cvt_f32_u32_e32 v0, s14
	s_sub_i32 s16, 0, s14
	s_mulk_i32 s1, 0xe0
	s_sub_i32 s0, s0, s1
	v_rcp_iflag_f32_e32 v0, v0
	s_abs_i32 s1, s0
	s_xor_b32 s15, s0, s13
	s_ashr_i32 s15, s15, 31
	v_mul_f32_e32 v0, 0x4f7ffffe, v0
	v_cvt_u32_f32_e32 v0, v0
	s_nop 0
	v_readfirstlane_b32 s17, v0
	s_mul_i32 s16, s16, s17
	s_mul_hi_u32 s16, s17, s16
	s_add_i32 s17, s17, s16
	s_mul_hi_u32 s16, s1, s17
	s_mul_i32 s17, s16, s14
	s_sub_i32 s1, s1, s17
	s_add_i32 s18, s16, 1
	s_sub_i32 s17, s1, s14
	s_cmp_ge_u32 s1, s14
	s_cselect_b32 s16, s18, s16
	s_cselect_b32 s1, s17, s1
	s_add_i32 s17, s16, 1
	s_cmp_ge_u32 s1, s14
	s_cselect_b32 s1, s17, s16
	s_xor_b32 s1, s1, s15
	s_sub_i32 s16, s1, s15
	s_mul_i32 s1, s16, s13
	s_sub_i32 s0, s0, s1
	s_add_i32 s18, s12, s0
	s_sub_i32 s0, s16, 14
	s_cmp_lt_i32 s16, 14
	s_cselect_b32 s0, s16, s0
	s_cselect_b32 s1, 0, 1
	s_lshl_b32 s0, s0, 1
	s_or_b32 s16, s0, s1
